# v33 + prologue RMSNorm: row-invariant gain vector pieces loaded once before the row loop instead of seven dependent loads per row
# speedup vs baseline: 1.0011x; 1.0011x over previous
.LBB0_67:
	s_cmpk_gt_i32 s6, 0x1fff
	s_cbranch_scc1 .LBB0_70
	v_ashrrev_i32_e32 v1, 31, v0
	v_lshlrev_b32_e32 v2, 2, v0
	v_readlane_b32 s16, v254, 10
	v_xor_b32_e32 v34, 4, v2
	v_xor_b32_e32 v35, 8, v2
	v_xor_b32_e32 v36, 16, v2
	v_xor_b32_e32 v37, 32, v2
	v_xor_b32_e32 v38, 64, v2
	v_xor_b32_e32 v39, 0x80, v2
	v_lshlrev_b64 v[2:3], 4, v[0:1]
	v_readlane_b32 s18, v254, 12
	v_readlane_b32 s19, v254, 13
	s_mov_b64 s[10:11], 0x1400
	s_ashr_i32 s7, s6, 31
	v_lshl_add_u64 v[20:21], s[18:19], 0, v[2:3]
	v_lshl_add_u64 v[24:25], v[20:21], 0, s[10:11]
	s_mov_b64 s[10:11], 0x1800
	v_lshl_add_u64 v[26:27], v[20:21], 0, s[10:11]
	s_mov_b64 s[10:11], 0x1c00
	v_lshl_add_u64 v[28:29], v[20:21], 0, s[10:11]
	s_lshl_b64 s[10:11], s[6:7], 12
	s_add_u32 s10, s76, s10
	s_addc_u32 s11, s77, s11
	v_lshl_add_u64 v[0:1], v[0:1], 3, s[10:11]
	s_mov_b64 s[10:11], 0x8420000
	s_ashr_i32 s9, s8, 31
	v_lshl_add_u64 v[30:31], v[0:1], 0, s[10:11]
	s_lshl_b64 s[10:11], s[8:9], 12
	s_lshl_b64 s[12:13], s[6:7], 13
	v_readlane_b32 s17, v254, 11
	s_add_u32 s12, s16, s12
	s_addc_u32 s13, s17, s13
	s_mov_b64 s[0:1], 0x1000
	v_lshl_add_u64 v[0:1], s[12:13], 0, v[2:3]
	v_lshl_add_u64 v[22:23], v[20:21], 0, s[0:1]
	v_lshl_add_u64 v[32:33], v[0:1], 0, s[0:1]
	s_lshl_b64 s[12:13], s[8:9], 13
	v_mov_b32_e32 v40, 0x358637bd
	s_mov_b32 s7, 0xf800000
	v_mov_b32_e32 v41, 0x260
	v_readlane_b32 s20, v254, 14
	v_readlane_b32 s21, v254, 15
	v_readlane_b32 s22, v254, 16
	v_readlane_b32 s23, v254, 17
	v_readlane_b32 s24, v254, 18
	v_readlane_b32 s25, v254, 19
	v_readlane_b32 s26, v254, 20
	v_readlane_b32 s27, v254, 21
	v_readlane_b32 s28, v254, 22
	v_readlane_b32 s29, v254, 23
	v_readlane_b32 s30, v254, 24
	v_readlane_b32 s31, v254, 25
	global_load_dwordx4 v[94:97], v[20:21], off offset:1024
	global_load_dwordx4 v[98:101], v[20:21], off offset:2048
	global_load_dwordx4 v[102:105], v[20:21], off offset:3072
	global_load_dwordx4 v[106:109], v[22:23], off
	global_load_dwordx4 v[110:113], v[24:25], off
	global_load_dwordx4 v[114:117], v[26:27], off
	global_load_dwordx4 v[118:121], v[28:29], off
	s_waitcnt vmcnt(0)
.LBB0_69:
	global_load_dwordx4 v[42:45], v[32:33], off offset:-4096
	global_load_dwordx4 v[8:11], v[32:33], off offset:-3072
	global_load_dwordx4 v[46:49], v[32:33], off offset:-2048
	global_load_dwordx4 v[4:7], v[32:33], off
	global_load_dwordx4 v[50:53], v[32:33], off offset:-1024
	global_load_dwordx4 v[16:19], v[32:33], off offset:1024
	global_load_dwordx4 v[0:3], v[32:33], off offset:3072
	global_load_dwordx4 v[12:15], v[32:33], off offset:2048
	global_load_dwordx4 v[54:57], v[20:21], off
	s_add_i32 s6, s6, s8
	v_lshl_add_u64 v[32:33], v[32:33], 0, s[12:13]
	s_cmpk_lt_i32 s6, 0x2000
	s_waitcnt vmcnt(8)
	v_mov_b32_e32 v60, v43
	s_waitcnt vmcnt(7)
	v_mov_b32_e32 v61, v9
	v_mov_b32_e32 v64, v45
	v_mov_b32_e32 v65, v11
	v_mov_b32_e32 v58, v42
	v_mov_b32_e32 v59, v8
	v_mov_b32_e32 v62, v44
	v_mov_b32_e32 v63, v10
	s_waitcnt vmcnt(6)
	v_pk_mul_f32 v[66:67], v[48:49], v[48:49]
	v_pk_mul_f32 v[68:69], v[46:47], v[46:47]
	v_pk_mul_f32 v[60:61], v[60:61], v[60:61]
	v_pk_mul_f32 v[64:65], v[64:65], v[64:65]
	v_pk_mov_b32 v[82:83], v[68:69], v[66:67] op_sel:[1,0]
	v_mov_b32_e32 v69, v67
	v_pk_fma_f32 v[58:59], v[58:59], v[58:59], v[60:61]
	v_pk_fma_f32 v[60:61], v[62:63], v[62:63], v[64:65]
	s_waitcnt vmcnt(4)
	v_mul_f32_e32 v70, v51, v51
	v_mul_f32_e32 v72, v53, v53
	v_pk_add_f32 v[62:63], v[82:83], v[68:69]
	v_pk_add_f32 v[58:59], v[58:59], v[60:61]
	v_mul_f32_e32 v81, v4, v4
	v_mul_f32_e32 v84, v5, v5
	v_mul_f32_e32 v85, v6, v6
	v_mul_f32_e32 v86, v7, v7
	v_pk_fma_f32 v[66:67], v[50:51], v[50:51], v[70:71] op_sel_hi:[1,1,0]
	v_pk_fma_f32 v[70:71], v[52:53], v[52:53], v[72:73] op_sel_hi:[1,1,0]
	v_pk_add_f32 v[60:61], v[62:63], v[62:63] op_sel:[0,1] op_sel_hi:[1,0]
	v_pk_add_f32 v[58:59], v[58:59], v[58:59] op_sel:[0,1] op_sel_hi:[1,0]
	s_waitcnt vmcnt(3)
	v_pk_mul_f32 v[74:75], v[18:19], v[18:19]
	v_pk_mul_f32 v[76:77], v[16:17], v[16:17]
	v_mov_b32_e32 v67, v85
	v_mov_b32_e32 v71, v86
	v_mov_b32_e32 v61, v84
	v_mov_b32_e32 v59, v81
	v_pk_mov_b32 v[72:73], v[76:77], v[74:75] op_sel:[1,0]
	v_mov_b32_e32 v77, v75
	v_pk_add_f32 v[62:63], v[66:67], v[70:71]
	v_pk_add_f32 v[58:59], v[58:59], v[60:61]
	s_waitcnt vmcnt(1)
	v_mul_f32_e32 v78, v13, v13
	v_mul_f32_e32 v80, v15, v15
	v_pk_add_f32 v[64:65], v[72:73], v[76:77]
	v_pk_add_f32 v[58:59], v[58:59], v[62:63]
	v_mul_f32_e32 v87, v0, v0
	v_mul_f32_e32 v88, v1, v1
	v_mul_f32_e32 v89, v2, v2
	v_mul_f32_e32 v90, v3, v3
	v_pk_fma_f32 v[74:75], v[12:13], v[12:13], v[78:79] op_sel_hi:[1,1,0]
	v_pk_fma_f32 v[78:79], v[14:15], v[14:15], v[80:81] op_sel_hi:[1,1,0]
	v_pk_add_f32 v[64:65], v[64:65], v[64:65] op_sel:[0,1] op_sel_hi:[1,0]
	v_pk_add_f32 v[58:59], v[58:59], v[58:59] op_sel:[0,1] op_sel_hi:[1,0]
	v_mov_b32_e32 v75, v89
	v_mov_b32_e32 v79, v90
	v_mov_b32_e32 v65, v88
	v_mov_b32_e32 v59, v87
	v_pk_add_f32 v[66:67], v[74:75], v[78:79]
	v_pk_add_f32 v[58:59], v[58:59], v[64:65]
	s_nop 0
	v_pk_add_f32 v[58:59], v[58:59], v[66:67]
	s_nop 0
	v_add_f32_e32 v58, v58, v59
	ds_bpermute_b32 v59, v34, v58
	s_waitcnt lgkmcnt(0)
	v_add_f32_e32 v58, v58, v59
	ds_bpermute_b32 v59, v35, v58
	s_waitcnt lgkmcnt(0)
	v_add_f32_e32 v58, v58, v59
	ds_bpermute_b32 v59, v36, v58
	s_waitcnt lgkmcnt(0)
	v_add_f32_e32 v58, v58, v59
	ds_bpermute_b32 v59, v37, v58
	s_waitcnt lgkmcnt(0)
	v_add_f32_e32 v58, v58, v59
	ds_bpermute_b32 v59, v38, v58
	s_waitcnt lgkmcnt(0)
	v_add_f32_e32 v58, v58, v59
	ds_bpermute_b32 v59, v39, v58
	s_waitcnt lgkmcnt(0)
	v_add_f32_e32 v58, v58, v59
	v_fmamk_f32 v58, v58, 0x3a000000, v40
	v_mul_f32_e32 v59, 0x4f800000, v58
	v_cmp_gt_f32_e32 vcc, s7, v58
	s_nop 1
	v_cndmask_b32_e32 v58, v58, v59, vcc
	v_sqrt_f32_e32 v59, v58
	s_nop 0
	v_add_u32_e32 v60, -1, v59
	v_add_u32_e32 v61, 1, v59
	v_fma_f32 v62, -v60, v59, v58
	v_fma_f32 v63, -v61, v59, v58
	v_cmp_ge_f32_e64 s[0:1], 0, v62
	s_nop 1
	v_cndmask_b32_e64 v59, v59, v60, s[0:1]
	v_cmp_lt_f32_e64 s[0:1], 0, v63
	s_nop 1
	v_cndmask_b32_e64 v59, v59, v61, s[0:1]
	v_mul_f32_e32 v60, 0x37800000, v59
	v_cndmask_b32_e32 v59, v59, v60, vcc
	v_cmp_class_f32_e32 vcc, v58, v41
	s_nop 1
	v_cndmask_b32_e32 v58, v59, v58, vcc
	v_div_scale_f32 v59, s[0:1], v58, v58, 1.0
	v_rcp_f32_e32 v61, v59
	v_div_scale_f32 v60, vcc, 1.0, v58, 1.0
	v_fma_f32 v62, -v59, v61, 1.0
	v_fmac_f32_e32 v61, v62, v61
	v_mul_f32_e32 v62, v60, v61
	v_fma_f32 v63, -v59, v62, v60
	v_fmac_f32_e32 v62, v63, v61
	v_fma_f32 v59, -v59, v62, v60
	v_div_fmas_f32 v59, v59, v61, v62
	v_div_fixup_f32 v58, v59, v58, 1.0
	v_pk_mul_f32 v[42:43], v[42:43], v[58:59] op_sel_hi:[1,0]
	v_pk_mul_f32 v[44:45], v[44:45], v[58:59] op_sel_hi:[1,0]
	s_waitcnt vmcnt(0)
	v_pk_mul_f32 v[42:43], v[54:55], v[42:43]
	v_pk_mul_f32 v[44:45], v[56:57], v[44:45]
	v_cvt_pk_bf16_f32 v42, v42, v43
	v_cvt_pk_bf16_f32 v43, v44, v45
	global_store_dwordx2 v[30:31], v[42:43], off
	v_mov_b32_e32 v42, v94
	v_mov_b32_e32 v43, v95
	v_mov_b32_e32 v44, v96
	v_mov_b32_e32 v45, v97
	v_pk_mul_f32 v[8:9], v[8:9], v[58:59] op_sel_hi:[1,0]
	v_pk_mul_f32 v[10:11], v[10:11], v[58:59] op_sel_hi:[1,0]
	v_pk_mul_f32 v[4:5], v[4:5], v[58:59] op_sel_hi:[1,0]
	v_pk_mul_f32 v[6:7], v[6:7], v[58:59] op_sel_hi:[1,0]
	v_pk_mul_f32 v[0:1], v[0:1], v[58:59] op_sel_hi:[1,0]
	v_pk_mul_f32 v[2:3], v[2:3], v[58:59] op_sel_hi:[1,0]
	s_nop 0
	v_pk_mul_f32 v[8:9], v[42:43], v[8:9]
	v_pk_mul_f32 v[10:11], v[44:45], v[10:11]
	v_cvt_pk_bf16_f32 v8, v8, v9
	v_cvt_pk_bf16_f32 v9, v10, v11
	global_store_dwordx2 v[30:31], v[8:9], off offset:512
	v_mov_b32_e32 v8, v98
	v_mov_b32_e32 v9, v99
	v_mov_b32_e32 v10, v100
	v_mov_b32_e32 v11, v101
	v_pk_mul_f32 v[42:43], v[46:47], v[58:59] op_sel_hi:[1,0]
	v_pk_mul_f32 v[44:45], v[48:49], v[58:59] op_sel_hi:[1,0]
	s_nop 0
	v_pk_mul_f32 v[8:9], v[8:9], v[42:43]
	v_pk_mul_f32 v[10:11], v[10:11], v[44:45]
	v_cvt_pk_bf16_f32 v8, v8, v9
	v_cvt_pk_bf16_f32 v9, v10, v11
	global_store_dwordx2 v[30:31], v[8:9], off offset:1024
	v_mov_b32_e32 v8, v102
	v_mov_b32_e32 v9, v103
	v_mov_b32_e32 v10, v104
	v_mov_b32_e32 v11, v105
	v_pk_mul_f32 v[42:43], v[50:51], v[58:59] op_sel_hi:[1,0]
	v_pk_mul_f32 v[44:45], v[52:53], v[58:59] op_sel_hi:[1,0]
	s_nop 0
	v_pk_mul_f32 v[8:9], v[8:9], v[42:43]
	v_pk_mul_f32 v[10:11], v[10:11], v[44:45]
	v_cvt_pk_bf16_f32 v8, v8, v9
	v_cvt_pk_bf16_f32 v9, v10, v11
	global_store_dwordx2 v[30:31], v[8:9], off offset:1536
	v_mov_b32_e32 v8, v106
	v_mov_b32_e32 v9, v107
	v_mov_b32_e32 v10, v108
	v_mov_b32_e32 v11, v109
	s_nop 0
	v_pk_mul_f32 v[4:5], v[4:5], v[8:9]
	v_pk_mul_f32 v[6:7], v[6:7], v[10:11]
	v_cvt_pk_bf16_f32 v4, v4, v5
	v_cvt_pk_bf16_f32 v5, v6, v7
	global_store_dwordx2 v[30:31], v[4:5], off offset:2048
	v_mov_b32_e32 v4, v110
	v_mov_b32_e32 v5, v111
	v_mov_b32_e32 v6, v112
	v_mov_b32_e32 v7, v113
	v_pk_mul_f32 v[8:9], v[16:17], v[58:59] op_sel_hi:[1,0]
	v_pk_mul_f32 v[10:11], v[18:19], v[58:59] op_sel_hi:[1,0]
	s_nop 0
	v_pk_mul_f32 v[4:5], v[8:9], v[4:5]
	v_pk_mul_f32 v[6:7], v[10:11], v[6:7]
	v_cvt_pk_bf16_f32 v4, v4, v5
	v_cvt_pk_bf16_f32 v5, v6, v7
	global_store_dwordx2 v[30:31], v[4:5], off offset:2560
	v_mov_b32_e32 v4, v114
	v_mov_b32_e32 v5, v115
	v_mov_b32_e32 v6, v116
	v_mov_b32_e32 v7, v117
	v_pk_mul_f32 v[8:9], v[12:13], v[58:59] op_sel_hi:[1,0]
	v_pk_mul_f32 v[10:11], v[14:15], v[58:59] op_sel_hi:[1,0]
	s_nop 0
	v_pk_mul_f32 v[4:5], v[8:9], v[4:5]
	v_pk_mul_f32 v[6:7], v[10:11], v[6:7]
	v_cvt_pk_bf16_f32 v4, v4, v5
	v_cvt_pk_bf16_f32 v5, v6, v7
	global_store_dwordx2 v[30:31], v[4:5], off offset:3072
	v_mov_b32_e32 v4, v118
	v_mov_b32_e32 v5, v119
	v_mov_b32_e32 v6, v120
	v_mov_b32_e32 v7, v121
	s_nop 0
	v_pk_mul_f32 v[0:1], v[0:1], v[4:5]
	v_pk_mul_f32 v[2:3], v[2:3], v[6:7]
	v_cvt_pk_bf16_f32 v0, v0, v1
	v_cvt_pk_bf16_f32 v1, v2, v3
	global_store_dwordx2 v[30:31], v[0:1], off offset:3584
	v_lshl_add_u64 v[30:31], v[30:31], 0, s[10:11]
	s_cbranch_scc1 .LBB0_69
